# P0 weight items: the 8 per-lane norm-scale loads per item issued together (one wait) instead of 4-8 serialized round trips; on top of v23
# baseline (speedup 1.0000x reference)
; #define LAS __attribute__((address_space(3)))
; #define LDS_WAIT() asm volatile("s_waitcnt lgkmcnt(0)" ::: "memory")
; __device__ __forceinline__ void p0_item_store(const P0Item& I, const float (&wv)[32], LAS float* scr, int lane) {
; #pragma unroll
;     for (int i = 0; i < 8; ++i) { const int kk = 8 * i + (lane >> 3); const float s = I.scale ? I.scale[I.k0 + kk] : 1.f; LAS float* d = scr + kk * 33 + 4 * (lane & 7);
;         d[0] = wv[4 * i] * s; d[1] = wv[4 * i + 1] * s; d[2] = wv[4 * i + 2] * s; d[3] = wv[4 * i + 3] * s; }
;     LDS_WAIT(); asm volatile("" ::: "memory");
.LBB0_75:
	v_ashrrev_i32_e32 v139, 31, v138
	v_cndmask_b32_e64 v142, 0, 1, s[22:23]
	v_mov_b32_e32 v140, 1.0
	v_cmp_ne_u32_e64 s[8:9], 1, v142
	s_andn2_b64 vcc, exec, s[22:23]
	v_lshl_add_u64 v[138:139], v[138:139], 2, s[20:21]
	v_mov_b32_e32 v142, 1.0
	s_waitcnt vmcnt(7)
	v_mov_b32_e32 v144, v124
	v_mov_b32_e32 v145, v125
	v_mov_b32_e32 v146, v126
	v_mov_b32_e32 v147, v127
	s_cbranch_vccnz .LBB0_77
	global_load_dword v146, v[138:139], off
	global_load_dword v142, v[138:139], off offset:32
	global_load_dword v172, v[138:139], off offset:64
	global_load_dword v173, v[138:139], off offset:96
	global_load_dword v174, v[138:139], off offset:128
	global_load_dword v175, v[138:139], off offset:160
	global_load_dword v176, v[138:139], off offset:192
	global_load_dword v177, v[138:139], off offset:224
	s_waitcnt vmcnt(0)
	v_pk_mul_f32 v[144:145], v[124:125], v[146:147] op_sel_hi:[1,0]
	v_pk_mul_f32 v[146:147], v[126:127], v[146:147] op_sel_hi:[1,0]
.LBB0_77:
	v_add_u32_e32 v163, v141, v148
	ds_write2_b32 v163, v144, v145 offset1:1
	ds_write2_b32 v163, v146, v147 offset0:2 offset1:3
	s_waitcnt vmcnt(0)
	v_pk_mul_f32 v[144:145], v[120:121], v[142:143] op_sel_hi:[1,0]
	v_add_u32_e32 v143, 0x420, v163
	ds_write2_b32 v143, v144, v145 offset1:1
	v_pk_mul_f32 v[142:143], v[122:123], v[142:143] op_sel_hi:[1,0]
	v_add_u32_e32 v144, 0x428, v163
	ds_write2_b32 v144, v142, v143 offset1:1
	s_and_b64 vcc, exec, s[8:9]
	v_mov_b32_e32 v142, v116
	v_mov_b32_e32 v143, v117
	v_mov_b32_e32 v144, v118
	v_mov_b32_e32 v145, v119
	s_cbranch_vccnz .LBB0_79
	v_mov_b32_e32 v144, v172
	v_mov_b32_e32 v140, v173
	s_waitcnt vmcnt(1)
	v_pk_mul_f32 v[142:143], v[116:117], v[144:145] op_sel_hi:[1,0]
	v_pk_mul_f32 v[144:145], v[118:119], v[144:145] op_sel_hi:[1,0]
.LBB0_79:
	ds_write2_b32 v158, v142, v143 offset1:1
	ds_write2_b32 v158, v144, v145 offset0:2 offset1:3
	s_waitcnt vmcnt(0)
	v_pk_mul_f32 v[142:143], v[112:113], v[140:141] op_sel_hi:[1,0]
	v_add_u32_e32 v144, 0x420, v158
	ds_write2_b32 v144, v142, v143 offset1:1
	v_pk_mul_f32 v[142:143], v[114:115], v[140:141] op_sel_hi:[1,0]
	v_add_u32_e32 v140, 0x428, v158
	ds_write2_b32 v140, v142, v143 offset1:1
	v_mov_b32_e32 v140, 1.0
	s_and_b64 vcc, exec, s[8:9]
	v_mov_b32_e32 v142, 1.0
	v_mov_b32_e32 v144, v108
	v_mov_b32_e32 v145, v109
	v_mov_b32_e32 v146, v110
	v_mov_b32_e32 v147, v111
	s_cbranch_vccnz .LBB0_81
	v_mov_b32_e32 v146, v174
	v_mov_b32_e32 v142, v175
	s_waitcnt vmcnt(1)
	v_pk_mul_f32 v[144:145], v[108:109], v[146:147] op_sel_hi:[1,0]
	v_pk_mul_f32 v[146:147], v[110:111], v[146:147] op_sel_hi:[1,0]
.LBB0_81:
	v_add_u32_e32 v160, 0x420, v159
	v_add_u32_e32 v161, 0x428, v159
	ds_write2_b32 v160, v144, v145 offset1:1
	ds_write2_b32 v161, v146, v147 offset1:1
	s_waitcnt vmcnt(0)
	v_pk_mul_f32 v[144:145], v[104:105], v[142:143] op_sel_hi:[1,0]
	v_add_u32_e32 v147, 0x840, v159
	v_pk_mul_f32 v[142:143], v[106:107], v[142:143] op_sel_hi:[1,0]
	v_add_u32_e32 v146, 0x848, v159
	ds_write2_b32 v147, v144, v145 offset1:1
	ds_write2_b32 v146, v142, v143 offset1:1
	s_and_b64 vcc, exec, s[8:9]
	v_mov_b32_e32 v142, v100
	v_mov_b32_e32 v143, v101
	v_mov_b32_e32 v144, v102
	v_mov_b32_e32 v145, v103
	s_cbranch_vccnz .LBB0_83
	v_mov_b32_e32 v144, v176
	v_mov_b32_e32 v140, v177
	s_waitcnt vmcnt(1)
	v_pk_mul_f32 v[142:143], v[100:101], v[144:145] op_sel_hi:[1,0]
	v_pk_mul_f32 v[144:145], v[102:103], v[144:145] op_sel_hi:[1,0]

; #define LAS __attribute__((address_space(3)))
; __device__ __forceinline__ void p0_item_store(const P0Item& I, const float (&wv)[32], LAS float* scr, int lane) {
; #pragma unroll
;     for (int i = 0; i < 8; ++i) { const int kk = 8 * i + (lane >> 3); const float s = I.scale ? I.scale[I.k0 + kk] : 1.f; LAS float* d = scr + kk * 33 + 4 * (lane & 7);
;         d[0] = wv[4 * i] * s; d[1] = wv[4 * i + 1] * s; d[2] = wv[4 * i + 2] * s; d[3] = wv[4 * i + 3] * s; }
.LBB0_99:
	s_cmp_lg_u64 s[20:21], 0
	s_cselect_b64 s[14:15], -1, 0
	s_cmp_eq_u64 s[20:21], 0
	s_cbranch_scc1 .LBB0_123
	v_add_u32_e32 v144, s82, v132
	v_ashrrev_i32_e32 v145, 31, v144
	v_lshl_add_u64 v[144:145], v[144:145], 2, s[20:21]
	global_load_dword v138, v[144:145], off
	global_load_dword v172, v[144:145], off offset:32
	global_load_dword v173, v[144:145], off offset:64
	global_load_dword v174, v[144:145], off offset:96
	global_load_dword v175, v[144:145], off offset:128
	global_load_dword v176, v[144:145], off offset:160
	global_load_dword v177, v[144:145], off offset:192
	global_load_dword v178, v[144:145], off offset:224
	s_waitcnt vmcnt(0)
	v_pk_mul_f32 v[164:165], v[68:69], v[138:139] op_sel_hi:[1,0]
	ds_write2_b32 v163, v164, v165 offset1:1
	v_pk_mul_f32 v[164:165], v[70:71], v[138:139] op_sel_hi:[1,0]
	v_mov_b32_e32 v138, v172
	ds_write2_b32 v163, v164, v165 offset0:2 offset1:3
	s_cbranch_execnz .LBB0_102

; #define LAS __attribute__((address_space(3)))
; __device__ __forceinline__ void p0_item_store(const P0Item& I, const float (&wv)[32], LAS float* scr, int lane) {
; #pragma unroll
;     for (int i = 0; i < 8; ++i) { const int kk = 8 * i + (lane >> 3); const float s = I.scale ? I.scale[I.k0 + kk] : 1.f; LAS float* d = scr + kk * 33 + 4 * (lane & 7);
;         d[0] = wv[4 * i] * s; d[1] = wv[4 * i + 1] * s; d[2] = wv[4 * i + 2] * s; d[3] = wv[4 * i + 3] * s; }
.LBB0_102:
	s_waitcnt vmcnt(0)
	v_pk_mul_f32 v[144:145], v[64:65], v[138:139] op_sel_hi:[1,0]
	v_add_u32_e32 v143, v141, v150
	ds_write2_b32 v143, v144, v145 offset1:1
	v_pk_mul_f32 v[144:145], v[66:67], v[138:139] op_sel_hi:[1,0]
	v_cndmask_b32_e64 v138, 0, 1, s[14:15]
	v_cmp_ne_u32_e64 s[10:11], 1, v138
	s_andn2_b64 vcc, exec, s[14:15]
	ds_write2_b32 v143, v144, v145 offset0:2 offset1:3
	s_cbranch_vccnz .LBB0_124
	s_ashr_i32 s83, s82, 31
	v_lshl_add_u64 v[144:145], s[82:83], 0, v[132:133]
	v_lshl_add_u64 v[144:145], v[144:145], 2, s[20:21]
	v_mov_b32_e32 v138, v173
	s_waitcnt vmcnt(0)
	v_pk_mul_f32 v[164:165], v[76:77], v[138:139] op_sel_hi:[1,0]
	ds_write2_b32 v158, v164, v165 offset1:1
	v_pk_mul_f32 v[164:165], v[78:79], v[138:139] op_sel_hi:[1,0]
	v_mov_b32_e32 v138, v174
	ds_write2_b32 v158, v164, v165 offset0:2 offset1:3
	s_cbranch_execnz .LBB0_105

; #define LAS __attribute__((address_space(3)))
; __device__ __forceinline__ void p0_item_store(const P0Item& I, const float (&wv)[32], LAS float* scr, int lane) {
; #pragma unroll
;     for (int i = 0; i < 8; ++i) { const int kk = 8 * i + (lane >> 3); const float s = I.scale ? I.scale[I.k0 + kk] : 1.f; LAS float* d = scr + kk * 33 + 4 * (lane & 7);
;         d[0] = wv[4 * i] * s; d[1] = wv[4 * i + 1] * s; d[2] = wv[4 * i + 2] * s; d[3] = wv[4 * i + 3] * s; }
.LBB0_105:
	s_waitcnt vmcnt(0)
	v_pk_mul_f32 v[144:145], v[72:73], v[138:139] op_sel_hi:[1,0]
	ds_write2_b32 v159, v144, v145 offset1:1
	v_pk_mul_f32 v[144:145], v[74:75], v[138:139] op_sel_hi:[1,0]
	s_and_b64 vcc, exec, s[10:11]
	ds_write2_b32 v159, v144, v145 offset0:2 offset1:3
	s_cbranch_vccnz .LBB0_125
	s_ashr_i32 s83, s82, 31
	v_lshl_add_u64 v[144:145], s[82:83], 0, v[132:133]
	v_lshl_add_u64 v[144:145], v[144:145], 2, s[20:21]
	v_mov_b32_e32 v138, v175
	s_waitcnt vmcnt(0)
	v_pk_mul_f32 v[164:165], v[84:85], v[138:139] op_sel_hi:[1,0]
	ds_write2_b32 v160, v164, v165 offset1:1
	v_pk_mul_f32 v[164:165], v[86:87], v[138:139] op_sel_hi:[1,0]
	v_mov_b32_e32 v138, v176
	ds_write2_b32 v161, v164, v165 offset1:1
	s_cbranch_execnz .LBB0_108

; #define LAS __attribute__((address_space(3)))
; __device__ __forceinline__ void p0_item_store(const P0Item& I, const float (&wv)[32], LAS float* scr, int lane) {
; #pragma unroll
;     for (int i = 0; i < 8; ++i) { const int kk = 8 * i + (lane >> 3); const float s = I.scale ? I.scale[I.k0 + kk] : 1.f; LAS float* d = scr + kk * 33 + 4 * (lane & 7);
;         d[0] = wv[4 * i] * s; d[1] = wv[4 * i + 1] * s; d[2] = wv[4 * i + 2] * s; d[3] = wv[4 * i + 3] * s; }
.LBB0_108:
	s_waitcnt vmcnt(0)
	v_pk_mul_f32 v[144:145], v[80:81], v[138:139] op_sel_hi:[1,0]
	ds_write2_b32 v147, v144, v145 offset1:1
	v_pk_mul_f32 v[144:145], v[82:83], v[138:139] op_sel_hi:[1,0]
	s_and_b64 vcc, exec, s[10:11]
	ds_write2_b32 v146, v144, v145 offset1:1
	s_cbranch_vccnz .LBB0_126
	s_ashr_i32 s83, s82, 31
	v_lshl_add_u64 v[144:145], s[82:83], 0, v[132:133]
	v_lshl_add_u64 v[144:145], v[144:145], 2, s[20:21]
	v_mov_b32_e32 v164, v177
	v_mov_b32_e32 v138, v178
	s_waitcnt vmcnt(1)
	v_pk_mul_f32 v[144:145], v[92:93], v[164:165] op_sel_hi:[1,0]
	v_pk_mul_f32 v[164:165], v[94:95], v[164:165] op_sel_hi:[1,0]
	ds_write2_b32 v162, v144, v145 offset1:1
	ds_write2_b32 v142, v164, v165 offset1:1
	s_cbranch_execnz .LBB0_111

; #define LAS __attribute__((address_space(3)))
; __device__ __forceinline__ void p0_item_store(const P0Item& I, const float (&wv)[32], LAS float* scr, int lane) {
; #pragma unroll
;     for (int i = 0; i < 8; ++i) { const int kk = 8 * i + (lane >> 3); const float s = I.scale ? I.scale[I.k0 + kk] : 1.f; LAS float* d = scr + kk * 33 + 4 * (lane & 7);
;         d[0] = wv[4 * i] * s; d[1] = wv[4 * i + 1] * s; d[2] = wv[4 * i + 2] * s; d[3] = wv[4 * i + 3] * s; }
.LBB0_112:
	s_and_b64 vcc, exec, s[8:9]
	s_cbranch_vccnz .LBB0_127
	v_add_u32_e32 v144, s86, v132
	v_ashrrev_i32_e32 v145, 31, v144
	v_lshl_add_u64 v[144:145], v[144:145], 2, s[20:21]
	global_load_dword v164, v[144:145], off
	global_load_dword v138, v[144:145], off offset:32
	global_load_dword v172, v[144:145], off offset:64
	global_load_dword v173, v[144:145], off offset:96
	global_load_dword v174, v[144:145], off offset:128
	global_load_dword v175, v[144:145], off offset:160
	global_load_dword v176, v[144:145], off offset:192
	global_load_dword v177, v[144:145], off offset:224
	s_waitcnt vmcnt(0)
	v_pk_mul_f32 v[144:145], v[124:125], v[164:165] op_sel_hi:[1,0]
	v_pk_mul_f32 v[164:165], v[126:127], v[164:165] op_sel_hi:[1,0]
	ds_write2_b32 v163, v144, v145 offset1:1
	ds_write2_b32 v163, v164, v165 offset0:2 offset1:3
	s_cbranch_execnz .LBB0_115

; #define LAS __attribute__((address_space(3)))
; __device__ __forceinline__ void p0_item_store(const P0Item& I, const float (&wv)[32], LAS float* scr, int lane) {
; #pragma unroll
;     for (int i = 0; i < 8; ++i) { const int kk = 8 * i + (lane >> 3); const float s = I.scale ? I.scale[I.k0 + kk] : 1.f; LAS float* d = scr + kk * 33 + 4 * (lane & 7);
;         d[0] = wv[4 * i] * s; d[1] = wv[4 * i + 1] * s; d[2] = wv[4 * i + 2] * s; d[3] = wv[4 * i + 3] * s; }
.LBB0_115:
	s_waitcnt vmcnt(0)
	v_pk_mul_f32 v[120:121], v[120:121], v[138:139] op_sel_hi:[1,0]
	v_add_u32_e32 v124, v141, v150
	ds_write2_b32 v124, v120, v121 offset1:1
	v_pk_mul_f32 v[120:121], v[122:123], v[138:139] op_sel_hi:[1,0]
	s_and_b64 vcc, exec, s[8:9]
	ds_write2_b32 v124, v120, v121 offset0:2 offset1:3
	s_cbranch_vccnz .LBB0_128
	s_ashr_i32 s87, s86, 31
	v_lshl_add_u64 v[120:121], s[86:87], 0, v[132:133]
	v_lshl_add_u64 v[120:121], v[120:121], 2, s[20:21]
	v_mov_b32_e32 v122, v172
	s_nop 0
	v_mov_b32_e32 v120, v173
	s_waitcnt vmcnt(1)
	v_pk_mul_f32 v[124:125], v[116:117], v[122:123] op_sel_hi:[1,0]
	v_pk_mul_f32 v[122:123], v[118:119], v[122:123] op_sel_hi:[1,0]
	ds_write2_b32 v158, v124, v125 offset1:1
	ds_write2_b32 v158, v122, v123 offset0:2 offset1:3
	s_cbranch_execnz .LBB0_118

; #define LAS __attribute__((address_space(3)))
; __device__ __forceinline__ void p0_item_store(const P0Item& I, const float (&wv)[32], LAS float* scr, int lane) {
; #pragma unroll
;     for (int i = 0; i < 8; ++i) { const int kk = 8 * i + (lane >> 3); const float s = I.scale ? I.scale[I.k0 + kk] : 1.f; LAS float* d = scr + kk * 33 + 4 * (lane & 7);
;         d[0] = wv[4 * i] * s; d[1] = wv[4 * i + 1] * s; d[2] = wv[4 * i + 2] * s; d[3] = wv[4 * i + 3] * s; }
.LBB0_118:
	s_waitcnt vmcnt(0)
	v_pk_mul_f32 v[112:113], v[112:113], v[120:121] op_sel_hi:[1,0]
	ds_write2_b32 v159, v112, v113 offset1:1
	v_pk_mul_f32 v[112:113], v[114:115], v[120:121] op_sel_hi:[1,0]
	s_and_b64 vcc, exec, s[8:9]
	ds_write2_b32 v159, v112, v113 offset0:2 offset1:3
	s_cbranch_vccnz .LBB0_129
	s_ashr_i32 s87, s86, 31
	v_lshl_add_u64 v[112:113], s[86:87], 0, v[132:133]
	v_lshl_add_u64 v[112:113], v[112:113], 2, s[20:21]
	v_mov_b32_e32 v114, v174
	s_nop 0
	v_mov_b32_e32 v112, v175
	s_waitcnt vmcnt(1)
	v_pk_mul_f32 v[116:117], v[108:109], v[114:115] op_sel_hi:[1,0]
	v_pk_mul_f32 v[114:115], v[110:111], v[114:115] op_sel_hi:[1,0]
	ds_write2_b32 v160, v116, v117 offset1:1
	ds_write2_b32 v161, v114, v115 offset1:1
	s_cbranch_execnz .LBB0_121

; #define LAS __attribute__((address_space(3)))
; __device__ __forceinline__ void p0_item_store(const P0Item& I, const float (&wv)[32], LAS float* scr, int lane) {
; #pragma unroll
;     for (int i = 0; i < 8; ++i) { const int kk = 8 * i + (lane >> 3); const float s = I.scale ? I.scale[I.k0 + kk] : 1.f; LAS float* d = scr + kk * 33 + 4 * (lane & 7);
;         d[0] = wv[4 * i] * s; d[1] = wv[4 * i + 1] * s; d[2] = wv[4 * i + 2] * s; d[3] = wv[4 * i + 3] * s; }
.LBB0_121:
	s_waitcnt vmcnt(0)
	v_pk_mul_f32 v[104:105], v[104:105], v[112:113] op_sel_hi:[1,0]
	ds_write2_b32 v147, v104, v105 offset1:1
	v_pk_mul_f32 v[104:105], v[106:107], v[112:113] op_sel_hi:[1,0]
	s_and_b64 vcc, exec, s[8:9]
	ds_write2_b32 v146, v104, v105 offset1:1
	s_cbranch_vccnz .LBB0_130
	s_ashr_i32 s87, s86, 31
	v_lshl_add_u64 v[104:105], s[86:87], 0, v[132:133]
	v_lshl_add_u64 v[104:105], v[104:105], 2, s[20:21]
	v_mov_b32_e32 v106, v176
	s_nop 0
	v_mov_b32_e32 v104, v177
	s_waitcnt vmcnt(1)
	v_pk_mul_f32 v[108:109], v[100:101], v[106:107] op_sel_hi:[1,0]
	v_pk_mul_f32 v[106:107], v[102:103], v[106:107] op_sel_hi:[1,0]
	ds_write2_b32 v162, v108, v109 offset1:1
	ds_write2_b32 v142, v106, v107 offset1:1
	s_cbranch_execnz .LBB0_47
	s_branch .LBB0_46
